# P7 tail K-loop pipelined + XCD-aware tail item order; grid-barrier non-leader L1 invalidate issued before polling; P2y GLA item remap balancing rebuild steps
# speedup vs baseline: 1.0250x; 1.0250x over previous
.LBB0_318:
	s_or_b64 exec, exec, s[12:13]
	v_cvt_f32_u32_e32 v4, v2
	s_waitcnt vmcnt(0)
	v_readfirstlane_b32 s4, v3
	v_sub_u32_e32 v3, 0, v2
	v_rcp_iflag_f32_e32 v4, v4
	v_add_u32_e32 v5, s4, v1
	v_mul_f32_e32 v4, 0x4f7ffffe, v4
	v_cvt_u32_f32_e32 v4, v4
	v_mul_lo_u32 v1, v3, v4
	v_mul_hi_u32 v1, v4, v1
	v_add_u32_e32 v1, v4, v1
	v_mul_hi_u32 v1, v5, v1
	v_mul_lo_u32 v3, v1, v2
	v_sub_u32_e32 v3, v5, v3
	v_add_u32_e32 v4, 1, v1
	v_cmp_ge_u32_e32 vcc, v3, v2
	s_nop 1
	v_cndmask_b32_e32 v1, v1, v4, vcc
	v_sub_u32_e32 v4, v3, v2
	v_cndmask_b32_e32 v3, v3, v4, vcc
	v_add_u32_e32 v4, 1, v1
	v_cmp_ge_u32_e32 vcc, v3, v2
	v_add_u32_e32 v3, 1, v5
	s_nop 0
	v_cndmask_b32_e32 v1, v1, v4, vcc
	v_mul_lo_u32 v4, v2, v1
	v_add_u32_e32 v2, v4, v2
	v_cmp_ne_u32_e32 vcc, v3, v2
	s_and_saveexec_b64 s[4:5], vcc
	s_xor_b64 s[4:5], exec, s[4:5]
	s_cbranch_execz .LBB0_332
	s_waitcnt lgkmcnt(0)
	buffer_inv sc1
	v_mov_b32_e32 v0, 0x2000
	global_load_dword v0, v0, s[2:3] offset:1024 sc1
	s_add_u32 s16, s2, 0x2400
	s_addc_u32 s17, s3, 0
	s_waitcnt vmcnt(0)
	v_cmp_eq_u32_e32 vcc, v0, v1
	s_and_saveexec_b64 s[12:13], vcc
	s_cbranch_execz .LBB0_331
	s_add_u32 s14, s92, 0x80200
	s_addc_u32 s15, s93, 0
	s_mov_b32 s28, 1
	s_mov_b64 s[18:19], 0
	v_mov_b32_e32 v0, 0
	s_branch .LBB0_322

.LBB0_331:
	s_or_b64 exec, exec, s[12:13]
	s_waitcnt vmcnt(0)
	s_waitcnt vmcnt(0)

.LBB0_496:
	s_or_b64 exec, exec, s[10:11]
	v_cvt_f32_u32_e32 v4, v2
	s_waitcnt vmcnt(0)
	v_readfirstlane_b32 s8, v3
	v_sub_u32_e32 v3, 0, v2
	v_rcp_iflag_f32_e32 v4, v4
	v_add_u32_e32 v5, s8, v1
	v_mul_f32_e32 v4, 0x4f7ffffe, v4
	v_cvt_u32_f32_e32 v4, v4
	v_mul_lo_u32 v1, v3, v4
	v_mul_hi_u32 v1, v4, v1
	v_add_u32_e32 v1, v4, v1
	v_mul_hi_u32 v1, v5, v1
	v_mul_lo_u32 v3, v1, v2
	v_sub_u32_e32 v3, v5, v3
	v_add_u32_e32 v4, 1, v1
	v_cmp_ge_u32_e32 vcc, v3, v2
	s_nop 1
	v_cndmask_b32_e32 v1, v1, v4, vcc
	v_sub_u32_e32 v4, v3, v2
	v_cndmask_b32_e32 v3, v3, v4, vcc
	v_add_u32_e32 v4, 1, v1
	v_cmp_ge_u32_e32 vcc, v3, v2
	v_add_u32_e32 v3, 1, v5
	s_nop 0
	v_cndmask_b32_e32 v1, v1, v4, vcc
	v_mul_lo_u32 v4, v2, v1
	v_add_u32_e32 v2, v4, v2
	v_cmp_ne_u32_e32 vcc, v3, v2
	s_and_saveexec_b64 s[8:9], vcc
	s_xor_b64 s[8:9], exec, s[8:9]
	s_cbranch_execz .LBB0_510
	s_waitcnt lgkmcnt(0)
	buffer_inv sc1
	v_mov_b32_e32 v0, 0x2000
	global_load_dword v0, v0, s[2:3] offset:1024 sc1
	s_add_u32 s14, s2, 0x2400
	s_addc_u32 s15, s3, 0
	s_waitcnt vmcnt(0)
	v_cmp_eq_u32_e32 vcc, v0, v1
	s_and_saveexec_b64 s[10:11], vcc
	s_cbranch_execz .LBB0_509
	s_add_u32 s12, s92, 0x80200
	s_addc_u32 s13, s93, 0
	s_mov_b32 s26, 1
	s_mov_b64 s[16:17], 0
	v_mov_b32_e32 v0, 0
	s_branch .LBB0_500

.LBB0_509:
	s_or_b64 exec, exec, s[10:11]
	s_waitcnt vmcnt(0)
	s_waitcnt vmcnt(0)

.LBB0_666:
	s_or_b64 exec, exec, s[42:43]
	v_cvt_f32_u32_e32 v4, v2
	s_waitcnt vmcnt(0)
	v_readfirstlane_b32 s0, v3
	v_sub_u32_e32 v3, 0, v2
	v_rcp_iflag_f32_e32 v4, v4
	v_add_u32_e32 v5, s0, v1
	v_mul_f32_e32 v4, 0x4f7ffffe, v4
	v_cvt_u32_f32_e32 v4, v4
	v_mul_lo_u32 v1, v3, v4
	v_mul_hi_u32 v1, v4, v1
	v_add_u32_e32 v1, v4, v1
	v_mul_hi_u32 v1, v5, v1
	v_mul_lo_u32 v3, v1, v2
	v_sub_u32_e32 v3, v5, v3
	v_add_u32_e32 v4, 1, v1
	v_cmp_ge_u32_e32 vcc, v3, v2
	s_nop 1
	v_cndmask_b32_e32 v1, v1, v4, vcc
	v_sub_u32_e32 v4, v3, v2
	v_cndmask_b32_e32 v3, v3, v4, vcc
	v_add_u32_e32 v4, 1, v1
	v_cmp_ge_u32_e32 vcc, v3, v2
	v_add_u32_e32 v3, 1, v5
	s_nop 0
	v_cndmask_b32_e32 v1, v1, v4, vcc
	v_mul_lo_u32 v4, v2, v1
	v_add_u32_e32 v2, v4, v2
	v_cmp_ne_u32_e32 vcc, v3, v2
	s_and_saveexec_b64 s[0:1], vcc
	s_xor_b64 s[44:45], exec, s[0:1]
	s_cbranch_execz .LBB0_680
	s_waitcnt lgkmcnt(0)
	buffer_inv sc1
	v_mov_b32_e32 v0, 0x2000
	global_load_dword v0, v0, s[2:3] offset:1024 sc1
	s_add_u32 s46, s2, 0x2400
	s_addc_u32 s47, s3, 0
	s_waitcnt vmcnt(0)
	v_cmp_eq_u32_e32 vcc, v0, v1
	s_and_saveexec_b64 s[0:1], vcc
	s_cbranch_execz .LBB0_679
	s_add_u32 s42, s92, 0x80200
	s_addc_u32 s43, s93, 0
	s_mov_b32 s72, 1
	s_mov_b64 s[48:49], 0
	v_mov_b32_e32 v0, 0
	s_branch .LBB0_670

.LBB0_679:
	s_or_b64 exec, exec, s[0:1]
	s_waitcnt vmcnt(0)
	s_waitcnt vmcnt(0)

.LBB0_740:
	s_and_b32 s98, s50, 7
	s_lshl_b32 s99, s98, 1
	s_lshr_b32 s98, s98, 2
	s_or_b32 s98, s99, s98
	s_and_b32 s98, s98, 7
	s_xor_b32 s98, s98, 7
	s_andn2_b32 s99, s50, 7
	s_or_b32 s98, s99, s98
	s_add_i32 s99, s98, 0xffffff00
	s_add_i32 s44, s98, 0xffffff00
	s_and_b32 s43, s98, 7
	s_and_b32 s42, s98, 7
	s_lshr_b32 s45, s44, 3
	s_cmp_eq_u32 s42, 0
	s_cbranch_scc1 .LBB0_745
	s_cmp_eq_u32 s43, 1
	s_cbranch_scc1 .LBB0_746
	s_lshr_b32 s47, s99, 3
	v_mov_b32_e32 v12, 0
	s_mul_i32 s0, s47, 0x1c0
	s_mul_i32 s47, s47, 7
	s_and_b32 s46, s43, 6
	s_mov_b32 s54, 0
	v_mov_b32_e32 v13, v12
	v_mov_b32_e32 v14, v12
	v_mov_b32_e32 v15, v12
	v_mov_b32_e32 v4, v12
	v_mov_b32_e32 v5, v12
	v_mov_b32_e32 v6, v12
	v_mov_b32_e32 v7, v12
	v_mov_b32_e32 v8, v12
	v_mov_b32_e32 v9, v12
	v_mov_b32_e32 v10, v12
	v_mov_b32_e32 v11, v12
	v_mov_b32_e32 v0, v12
	v_mov_b32_e32 v1, v12
	v_mov_b32_e32 v2, v12
	v_mov_b32_e32 v3, v12

.LBB0_762:
	s_lshl_b32 s0, s99, 6
	s_and_b32 s0, s0, 0xfffff800
	s_lshl_b32 s1, s43, 8
	v_add_f32_e32 v40, 0, v40
	s_or_b32 s43, s0, s1
	v_readlane_b32 s0, v248, 2
	v_add_f32_e32 v40, v40, v41
	s_lshl_b32 s52, s46, 1
	v_add_u32_e32 v190, s0, v162
	ds_write_b32 v190, v41 offset:13824
	ds_write_b32 v163, v40 offset:22016
	v_mov_b64_e32 v[40:41], s[76:77]
	v_mov_b64_e32 v[44:45], s[72:73]
	v_readlane_b32 s86, v249, 36
	v_lshl_add_u64 v[146:147], v[124:125], 0, s[52:53]
	s_mov_b32 s68, 0
	v_mov_b64_e32 v[42:43], s[78:79]
	v_mov_b64_e32 v[46:47], s[74:75]
	v_readlane_b32 s87, v249, 37
	s_branch .LBB0_765

.LBB0_873:
	s_or_b64 exec, exec, s[6:7]
	v_cvt_f32_u32_e32 v4, v2
	s_waitcnt vmcnt(0)
	v_readfirstlane_b32 s4, v3
	v_sub_u32_e32 v3, 0, v2
	v_rcp_iflag_f32_e32 v4, v4
	v_add_u32_e32 v5, s4, v1
	v_mul_f32_e32 v4, 0x4f7ffffe, v4
	v_cvt_u32_f32_e32 v4, v4
	v_mul_lo_u32 v1, v3, v4
	v_mul_hi_u32 v1, v4, v1
	v_add_u32_e32 v1, v4, v1
	v_mul_hi_u32 v1, v5, v1
	v_mul_lo_u32 v3, v1, v2
	v_sub_u32_e32 v3, v5, v3
	v_add_u32_e32 v4, 1, v1
	v_cmp_ge_u32_e32 vcc, v3, v2
	s_nop 1
	v_cndmask_b32_e32 v1, v1, v4, vcc
	v_sub_u32_e32 v4, v3, v2
	v_cndmask_b32_e32 v3, v3, v4, vcc
	v_add_u32_e32 v4, 1, v1
	v_cmp_ge_u32_e32 vcc, v3, v2
	v_add_u32_e32 v3, 1, v5
	s_nop 0
	v_cndmask_b32_e32 v1, v1, v4, vcc
	v_mul_lo_u32 v4, v2, v1
	v_add_u32_e32 v2, v4, v2
	v_cmp_ne_u32_e32 vcc, v3, v2
	s_and_saveexec_b64 s[4:5], vcc
	s_xor_b64 s[4:5], exec, s[4:5]
	s_cbranch_execz .LBB0_887
	s_waitcnt lgkmcnt(0)
	buffer_inv sc1
	v_mov_b32_e32 v0, 0x2000
	global_load_dword v0, v0, s[2:3] offset:1024 sc1
	s_add_u32 s10, s2, 0x2400
	s_addc_u32 s11, s3, 0
	s_waitcnt vmcnt(0)
	v_cmp_eq_u32_e32 vcc, v0, v1
	s_and_saveexec_b64 s[6:7], vcc
	s_cbranch_execz .LBB0_886
	s_add_u32 s8, s92, 0x80200
	s_addc_u32 s9, s93, 0
	s_mov_b32 s22, 1
	s_mov_b64 s[12:13], 0
	v_mov_b32_e32 v0, 0
	s_branch .LBB0_877

.LBB0_886:
	s_or_b64 exec, exec, s[6:7]
	s_waitcnt vmcnt(0)
	s_waitcnt vmcnt(0)

.LBB0_961:
	s_or_b64 exec, exec, s[8:9]
	v_cvt_f32_u32_e32 v4, v2
	s_waitcnt vmcnt(0)
	v_readfirstlane_b32 s6, v3
	v_sub_u32_e32 v3, 0, v2
	v_rcp_iflag_f32_e32 v4, v4
	v_add_u32_e32 v5, s6, v1
	v_mul_f32_e32 v4, 0x4f7ffffe, v4
	v_cvt_u32_f32_e32 v4, v4
	v_mul_lo_u32 v1, v3, v4
	v_mul_hi_u32 v1, v4, v1
	v_add_u32_e32 v1, v4, v1
	v_mul_hi_u32 v1, v5, v1
	v_mul_lo_u32 v3, v1, v2
	v_sub_u32_e32 v3, v5, v3
	v_add_u32_e32 v4, 1, v1
	v_cmp_ge_u32_e32 vcc, v3, v2
	s_nop 1
	v_cndmask_b32_e32 v1, v1, v4, vcc
	v_sub_u32_e32 v4, v3, v2
	v_cndmask_b32_e32 v3, v3, v4, vcc
	v_add_u32_e32 v4, 1, v1
	v_cmp_ge_u32_e32 vcc, v3, v2
	v_add_u32_e32 v3, 1, v5
	s_nop 0
	v_cndmask_b32_e32 v1, v1, v4, vcc
	v_mul_lo_u32 v4, v2, v1
	v_add_u32_e32 v2, v4, v2
	v_cmp_ne_u32_e32 vcc, v3, v2
	s_and_saveexec_b64 s[6:7], vcc
	s_xor_b64 s[6:7], exec, s[6:7]
	s_cbranch_execz .LBB0_975
	s_waitcnt lgkmcnt(0)
	buffer_inv sc1
	v_mov_b32_e32 v0, 0x2000
	global_load_dword v0, v0, s[2:3] offset:1024 sc1
	s_add_u32 s12, s2, 0x2400
	s_addc_u32 s13, s3, 0
	s_waitcnt vmcnt(0)
	v_cmp_eq_u32_e32 vcc, v0, v1
	s_and_saveexec_b64 s[8:9], vcc
	s_cbranch_execz .LBB0_974
	s_add_u32 s10, s92, 0x80200
	s_addc_u32 s11, s93, 0
	s_mov_b32 s24, 1
	s_mov_b64 s[14:15], 0
	v_mov_b32_e32 v0, 0
	s_branch .LBB0_965

.LBB0_974:
	s_or_b64 exec, exec, s[8:9]
	s_waitcnt vmcnt(0)
	s_waitcnt vmcnt(0)

.LBB0_1052:
	s_or_b64 exec, exec, s[8:9]
	v_cvt_f32_u32_e32 v4, v2
	s_waitcnt vmcnt(0)
	v_readfirstlane_b32 s6, v3
	v_sub_u32_e32 v3, 0, v2
	v_rcp_iflag_f32_e32 v4, v4
	v_add_u32_e32 v5, s6, v1
	v_mul_f32_e32 v4, 0x4f7ffffe, v4
	v_cvt_u32_f32_e32 v4, v4
	v_mul_lo_u32 v1, v3, v4
	v_mul_hi_u32 v1, v4, v1
	v_add_u32_e32 v1, v4, v1
	v_mul_hi_u32 v1, v5, v1
	v_mul_lo_u32 v3, v1, v2
	v_sub_u32_e32 v3, v5, v3
	v_add_u32_e32 v4, 1, v1
	v_cmp_ge_u32_e32 vcc, v3, v2
	s_nop 1
	v_cndmask_b32_e32 v1, v1, v4, vcc
	v_sub_u32_e32 v4, v3, v2
	v_cndmask_b32_e32 v3, v3, v4, vcc
	v_add_u32_e32 v4, 1, v1
	v_cmp_ge_u32_e32 vcc, v3, v2
	v_add_u32_e32 v3, 1, v5
	s_nop 0
	v_cndmask_b32_e32 v1, v1, v4, vcc
	v_mul_lo_u32 v4, v2, v1
	v_add_u32_e32 v2, v4, v2
	v_cmp_ne_u32_e32 vcc, v3, v2
	s_and_saveexec_b64 s[6:7], vcc
	s_xor_b64 s[6:7], exec, s[6:7]
	s_cbranch_execz .LBB0_1066
	s_waitcnt lgkmcnt(0)
	buffer_inv sc1
	v_mov_b32_e32 v0, 0x2000
	global_load_dword v0, v0, s[2:3] offset:1024 sc1
	s_add_u32 s12, s2, 0x2400
	s_addc_u32 s13, s3, 0
	s_waitcnt vmcnt(0)
	v_cmp_eq_u32_e32 vcc, v0, v1
	s_and_saveexec_b64 s[8:9], vcc
	s_cbranch_execz .LBB0_1065
	s_add_u32 s10, s92, 0x80200
	s_addc_u32 s11, s93, 0
	s_mov_b32 s26, 1
	s_mov_b64 s[16:17], 0
	v_mov_b32_e32 v0, 0
	s_branch .LBB0_1056

.LBB0_1168:
	s_or_b64 exec, exec, s[8:9]
	v_cvt_f32_u32_e32 v4, v2
	s_waitcnt vmcnt(0)
	v_readfirstlane_b32 s6, v3
	v_sub_u32_e32 v3, 0, v2
	v_rcp_iflag_f32_e32 v4, v4
	v_add_u32_e32 v5, s6, v1
	v_mul_f32_e32 v4, 0x4f7ffffe, v4
	v_cvt_u32_f32_e32 v4, v4
	v_mul_lo_u32 v1, v3, v4
	v_mul_hi_u32 v1, v4, v1
	v_add_u32_e32 v1, v4, v1
	v_mul_hi_u32 v1, v5, v1
	v_mul_lo_u32 v3, v1, v2
	v_sub_u32_e32 v3, v5, v3
	v_add_u32_e32 v4, 1, v1
	v_cmp_ge_u32_e32 vcc, v3, v2
	s_nop 1
	v_cndmask_b32_e32 v1, v1, v4, vcc
	v_sub_u32_e32 v4, v3, v2
	v_cndmask_b32_e32 v3, v3, v4, vcc
	v_add_u32_e32 v4, 1, v1
	v_cmp_ge_u32_e32 vcc, v3, v2
	v_add_u32_e32 v3, 1, v5
	s_nop 0
	v_cndmask_b32_e32 v1, v1, v4, vcc
	v_mul_lo_u32 v4, v2, v1
	v_add_u32_e32 v2, v4, v2
	v_cmp_ne_u32_e32 vcc, v3, v2
	s_and_saveexec_b64 s[6:7], vcc
	s_xor_b64 s[6:7], exec, s[6:7]
	s_cbranch_execz .LBB0_1182
	s_waitcnt lgkmcnt(0)
	buffer_inv sc1
	v_mov_b32_e32 v0, 0x2000
	global_load_dword v0, v0, s[2:3] offset:1024 sc1
	s_add_u32 s12, s2, 0x2400
	s_addc_u32 s13, s3, 0
	s_waitcnt vmcnt(0)
	v_cmp_eq_u32_e32 vcc, v0, v1
	s_and_saveexec_b64 s[8:9], vcc
	s_cbranch_execz .LBB0_1181
	s_add_u32 s10, s92, 0x80200
	s_addc_u32 s11, s93, 0
	s_mov_b32 s28, 1
	s_mov_b64 s[18:19], 0
	v_mov_b32_e32 v0, 0
	s_branch .LBB0_1172

.LBB0_1360:
	s_or_b64 exec, exec, s[8:9]
	v_cvt_f32_u32_e32 v4, v2
	s_waitcnt vmcnt(0)
	v_readfirstlane_b32 s6, v3
	v_sub_u32_e32 v3, 0, v2
	v_rcp_iflag_f32_e32 v4, v4
	v_add_u32_e32 v5, s6, v1
	v_mul_f32_e32 v4, 0x4f7ffffe, v4
	v_cvt_u32_f32_e32 v4, v4
	v_mul_lo_u32 v1, v3, v4
	v_mul_hi_u32 v1, v4, v1
	v_add_u32_e32 v1, v4, v1
	v_mul_hi_u32 v1, v5, v1
	v_mul_lo_u32 v3, v1, v2
	v_sub_u32_e32 v3, v5, v3
	v_add_u32_e32 v4, 1, v1
	v_cmp_ge_u32_e32 vcc, v3, v2
	s_nop 1
	v_cndmask_b32_e32 v1, v1, v4, vcc
	v_sub_u32_e32 v4, v3, v2
	v_cndmask_b32_e32 v3, v3, v4, vcc
	v_add_u32_e32 v4, 1, v1
	v_cmp_ge_u32_e32 vcc, v3, v2
	v_add_u32_e32 v3, 1, v5
	s_nop 0
	v_cndmask_b32_e32 v1, v1, v4, vcc
	v_mul_lo_u32 v4, v2, v1
	v_add_u32_e32 v2, v4, v2
	v_cmp_ne_u32_e32 vcc, v3, v2
	s_and_saveexec_b64 s[6:7], vcc
	s_xor_b64 s[6:7], exec, s[6:7]
	s_cbranch_execz .LBB0_1374
	s_waitcnt lgkmcnt(0)
	buffer_inv sc1
	v_mov_b32_e32 v0, 0x2000
	global_load_dword v0, v0, s[2:3] offset:1024 sc1
	s_add_u32 s12, s2, 0x2400
	s_addc_u32 s13, s3, 0
	s_waitcnt vmcnt(0)
	v_cmp_eq_u32_e32 vcc, v0, v1
	s_and_saveexec_b64 s[8:9], vcc
	s_cbranch_execz .LBB0_1373
	s_add_u32 s10, s92, 0x80200
	s_addc_u32 s11, s93, 0
	s_mov_b32 s33, 1
	s_mov_b64 s[22:23], 0
	v_mov_b32_e32 v0, 0
	s_branch .LBB0_1364

.LBB0_1486:
	s_cmp_lg_u32 s94, 0x100
	s_cbranch_scc1 .Lt7_noremap
	s_and_b32 s4, s69, 7
	s_lshr_b32 s5, s69, 3
	s_lshl_b32 s4, s4, 1
	s_lshr_b32 s1, s5, 4
	s_add_i32 s4, s4, s1
	s_lshl_b32 s4, s4, 2
	s_mov_b32 s2, 0xba983210
	s_mov_b32 s3, 0xf7edc654
	s_lshr_b64 s[2:3], s[2:3], s4
	s_and_b32 s2, s2, 15
	s_and_b32 s5, s5, 15
	s_lshl_b32 s2, s2, 4
	s_or_b32 s69, s2, s5
.Lt7_noremap:
	s_lshl_b32 s0, s40, 4
	s_cmp_ge_i32 s69, s0
	s_cbranch_scc1 .LBB0_1489
	v_readlane_b32 s4, v249, 16
	v_readlane_b32 s1, v250, 39
	s_mov_b32 s3, 0
	v_mov_b32_e32 v181, 0
	v_readlane_b32 s5, v249, 17
	s_mul_i32 s2, s1, 0x160
	s_lshl_b64 s[2:3], s[2:3], 1
	v_lshl_add_u64 v[0:1], s[4:5], 0, v[180:181]
	v_lshl_add_u64 v[40:41], v[0:1], 0, s[2:3]
	v_lshl_add_u64 v[0:1], s[78:79], 0, v[180:181]
	v_lshl_add_u64 v[42:43], v[0:1], 0, s[2:3]
	s_lshl_b32 s1, s69, 4
	s_movk_i32 s2, 0x1600
	s_mov_b32 s3, 0x16000
	s_mov_b32 s6, 0x2c000
	s_mov_b32 s7, 0x42000
	s_mov_b32 s8, 0x58000
	s_mov_b32 s9, 0x6e000
	s_mov_b32 s10, 0x84000
	s_mov_b32 s11, 0x9a000
	s_mov_b32 s12, 0xb0000
	s_mov_b32 s13, 0xc6000
	s_mov_b32 s14, 0xdc000
	s_mov_b32 s15, 0xf2000
	s_mov_b32 s18, 0x108000
	s_mov_b32 s19, 0x11e000
	s_mov_b32 s20, 0x134000
	s_mov_b32 s21, 0x14a000
	s_movk_i32 s22, 0x7fff
	s_mov_b32 s34, 0x16000
	s_mov_b32 s35, 0
	s_mov_b32 s36, 0x2c000
	s_mov_b32 s37, 0
	s_mov_b32 s38, 0x42000
	s_mov_b32 s39, 0
	s_mov_b32 s40, 0x58000
	s_mov_b32 s41, 0
	s_mov_b32 s42, 0x6e000
	s_mov_b32 s43, 0
	s_mov_b32 s44, 0x84000
	s_mov_b32 s45, 0
	s_mov_b32 s46, 0x9a000
	s_mov_b32 s47, 0
	s_mov_b32 s48, 0xb0000
	s_mov_b32 s49, 0
	s_mov_b32 s50, 0xc6000
	s_mov_b32 s51, 0
	s_mov_b32 s52, 0xdc000
	s_mov_b32 s53, 0
	s_mov_b32 s54, 0xf2000
	s_mov_b32 s55, 0
	s_mov_b32 s56, 0x108000
	s_mov_b32 s57, 0
	s_mov_b32 s58, 0x11e000
	s_mov_b32 s59, 0
	s_mov_b32 s60, 0x134000
	s_mov_b32 s61, 0
	s_mov_b32 s62, 0x14a000
	s_mov_b32 s63, 0
.LBB0_1488:
	s_ashr_i32 s23, s69, 4
	s_add_i32 s23, s23, s33
	s_ashr_i32 s24, s23, 31
	s_lshr_b32 s24, s24, 29
	s_add_i32 s24, s23, s24
	s_ashr_i32 s25, s24, 3
	s_and_b32 s24, s24, -8
	s_sub_i32 s23, s23, s24
	s_cmp_lt_i32 s23, 0
	s_cselect_b32 s24, 35, 34
	s_mul_i32 s23, s23, s24
	s_add_i32 s23, s23, s25
	s_ashr_i32 s24, s23, 31
	s_lshr_b32 s24, s24, 27
	s_add_i32 s24, s23, s24
	s_ashr_i32 s25, s24, 5
	s_andn2_b32 s24, s24, 31
	s_lshl_b32 s25, s25, 3
	s_sub_i32 s24, s23, s24
	s_sub_i32 s23, 0x44, s25
	s_min_i32 s23, s23, 8
	s_abs_i32 s28, s23
	v_cvt_f32_u32_e32 v0, s28
	s_sub_i32 s29, 0, s28
	s_abs_i32 s26, s24
	s_xor_b32 s27, s24, s23
	v_rcp_iflag_f32_e32 v0, v0
	s_ashr_i32 s27, s27, 31
	v_mul_f32_e32 v0, 0x4f7ffffe, v0
	v_cvt_u32_f32_e32 v0, v0
	s_nop 0
	v_readfirstlane_b32 s30, v0
	s_mul_i32 s29, s29, s30
	s_mul_hi_u32 s29, s30, s29
	s_add_i32 s30, s30, s29
	s_mul_hi_u32 s29, s26, s30
	s_mul_i32 s30, s29, s28
	s_sub_i32 s26, s26, s30
	s_add_i32 s31, s29, 1
	s_sub_i32 s30, s26, s28
	s_cmp_ge_u32 s26, s28
	s_cselect_b32 s29, s31, s29
	s_cselect_b32 s26, s30, s26
	s_add_i32 s30, s29, 1
	s_cmp_ge_u32 s26, s28
	s_cselect_b32 s26, s30, s29
	s_xor_b32 s26, s26, s27
	s_sub_i32 s26, s26, s27
	s_mul_i32 s27, s26, s23
	s_lshl_b32 s23, s26, 8
	s_sub_i32 s24, s24, s27
	v_or_b32_e32 v0, s23, v179
	s_add_i32 s26, s25, s24
	v_mad_i64_i32 v[44:45], s[24:25], v0, s2, v[42:43]
	s_and_b32 s28, s1, 0xf0
	s_lshl_b32 s24, s26, 8
	s_or_b32 s24, s24, s28
	v_or_b32_e32 v0, s24, v179
	v_mad_i64_i32 v[46:47], s[26:27], v0, s2, v[40:41]
	s_add_i32 s69, s69, s94
	s_add_i32 s1, s1, s72
	s_cmp_lt_i32 s69, s0
	v_lshl_add_u64 v[2:3], v[44:45], 0, s[34:35]
	v_lshl_add_u64 v[4:5], v[44:45], 0, s[36:37]
	v_lshl_add_u64 v[6:7], v[44:45], 0, s[38:39]
	v_lshl_add_u64 v[8:9], v[44:45], 0, s[40:41]
	v_lshl_add_u64 v[10:11], v[44:45], 0, s[42:43]
	v_lshl_add_u64 v[12:13], v[44:45], 0, s[44:45]
	v_lshl_add_u64 v[14:15], v[44:45], 0, s[46:47]
	global_load_dwordx4 v[16:19], v[46:47], off
	global_load_dwordx4 v[20:23], v[46:47], off offset:64
	global_load_dwordx4 v[48:51], v[44:45], off
	global_load_dwordx4 v[52:55], v[44:45], off offset:64
	global_load_dwordx4 v[56:59], v[2:3], off
	global_load_dwordx4 v[60:63], v[2:3], off offset:64
	global_load_dwordx4 v[64:67], v[4:5], off
	global_load_dwordx4 v[68:71], v[4:5], off offset:64
	global_load_dwordx4 v[72:75], v[6:7], off
	global_load_dwordx4 v[76:79], v[6:7], off offset:64
	global_load_dwordx4 v[80:83], v[8:9], off
	global_load_dwordx4 v[84:87], v[8:9], off offset:64
	global_load_dwordx4 v[88:91], v[10:11], off
	global_load_dwordx4 v[92:95], v[10:11], off offset:64
	global_load_dwordx4 v[96:99], v[12:13], off
	global_load_dwordx4 v[100:103], v[12:13], off offset:64
	global_load_dwordx4 v[104:107], v[14:15], off
	global_load_dwordx4 v[108:111], v[14:15], off offset:64
	v_lshl_add_u64 v[0:1], v[44:45], 0, s[48:49]
	v_lshl_add_u64 v[2:3], v[44:45], 0, s[50:51]
	v_lshl_add_u64 v[4:5], v[44:45], 0, s[52:53]
	v_lshl_add_u64 v[6:7], v[44:45], 0, s[54:55]
	v_lshl_add_u64 v[8:9], v[44:45], 0, s[56:57]
	v_lshl_add_u64 v[10:11], v[44:45], 0, s[58:59]
	v_lshl_add_u64 v[12:13], v[44:45], 0, s[60:61]
	v_lshl_add_u64 v[14:15], v[44:45], 0, s[62:63]
	global_load_dwordx4 v[112:115], v[0:1], off
	global_load_dwordx4 v[116:119], v[0:1], off offset:64
	global_load_dwordx4 v[120:123], v[2:3], off
	global_load_dwordx4 v[124:127], v[2:3], off offset:64
	global_load_dwordx4 v[128:131], v[4:5], off
	global_load_dwordx4 v[132:135], v[4:5], off offset:64
	global_load_dwordx4 v[136:139], v[6:7], off
	global_load_dwordx4 v[140:143], v[6:7], off offset:64
	global_load_dwordx4 v[144:147], v[8:9], off
	global_load_dwordx4 v[148:151], v[8:9], off offset:64
	global_load_dwordx4 v[152:155], v[10:11], off
	global_load_dwordx4 v[156:159], v[10:11], off offset:64
	global_load_dwordx4 v[160:163], v[12:13], off
	global_load_dwordx4 v[164:167], v[12:13], off offset:64
	global_load_dwordx4 v[168:171], v[14:15], off
	global_load_dwordx4 v[172:175], v[14:15], off offset:64
	s_waitcnt vmcnt(16)
	v_mfma_f32_16x16x32_bf16 v[32:35], v[16:19], v[48:51], 0
	v_mfma_f32_16x16x32_bf16 v[36:39], v[16:19], v[56:59], 0
	v_mfma_f32_16x16x32_bf16 v[180:183], v[16:19], v[64:67], 0
	v_mfma_f32_16x16x32_bf16 v[184:187], v[16:19], v[72:75], 0
	v_mfma_f32_16x16x32_bf16 v[188:191], v[16:19], v[80:83], 0
	v_mfma_f32_16x16x32_bf16 v[192:195], v[16:19], v[88:91], 0
	v_mfma_f32_16x16x32_bf16 v[196:199], v[16:19], v[96:99], 0
	v_mfma_f32_16x16x32_bf16 v[200:203], v[16:19], v[104:107], 0
	v_mfma_f32_16x16x32_bf16 v[32:35], v[20:23], v[52:55], v[32:35]
	v_mfma_f32_16x16x32_bf16 v[36:39], v[20:23], v[60:63], v[36:39]
	v_mfma_f32_16x16x32_bf16 v[180:183], v[20:23], v[68:71], v[180:183]
	v_mfma_f32_16x16x32_bf16 v[184:187], v[20:23], v[76:79], v[184:187]
	v_mfma_f32_16x16x32_bf16 v[188:191], v[20:23], v[84:87], v[188:191]
	v_mfma_f32_16x16x32_bf16 v[192:195], v[20:23], v[92:95], v[192:195]
	v_mfma_f32_16x16x32_bf16 v[196:199], v[20:23], v[100:103], v[196:199]
	v_mfma_f32_16x16x32_bf16 v[200:203], v[20:23], v[108:111], v[200:203]
	v_lshl_add_u64 v[2:3], v[44:45], 0, s[34:35]
	v_lshl_add_u64 v[4:5], v[44:45], 0, s[36:37]
	v_lshl_add_u64 v[6:7], v[44:45], 0, s[38:39]
	v_lshl_add_u64 v[8:9], v[44:45], 0, s[40:41]
	v_lshl_add_u64 v[10:11], v[44:45], 0, s[42:43]
	v_lshl_add_u64 v[12:13], v[44:45], 0, s[44:45]
	v_lshl_add_u64 v[14:15], v[44:45], 0, s[46:47]
	global_load_dwordx4 v[24:27], v[46:47], off offset:128
	global_load_dwordx4 v[28:31], v[46:47], off offset:192
	global_load_dwordx4 v[48:51], v[44:45], off offset:128
	global_load_dwordx4 v[52:55], v[44:45], off offset:192
	global_load_dwordx4 v[56:59], v[2:3], off offset:128
	global_load_dwordx4 v[60:63], v[2:3], off offset:192
	global_load_dwordx4 v[64:67], v[4:5], off offset:128
	global_load_dwordx4 v[68:71], v[4:5], off offset:192
	global_load_dwordx4 v[72:75], v[6:7], off offset:128
	global_load_dwordx4 v[76:79], v[6:7], off offset:192
	global_load_dwordx4 v[80:83], v[8:9], off offset:128
	global_load_dwordx4 v[84:87], v[8:9], off offset:192
	global_load_dwordx4 v[88:91], v[10:11], off offset:128
	global_load_dwordx4 v[92:95], v[10:11], off offset:192
	global_load_dwordx4 v[96:99], v[12:13], off offset:128
	global_load_dwordx4 v[100:103], v[12:13], off offset:192
	global_load_dwordx4 v[104:107], v[14:15], off offset:128
	global_load_dwordx4 v[108:111], v[14:15], off offset:192
	s_waitcnt vmcnt(18)
	v_mfma_f32_16x16x32_bf16 v[204:207], v[16:19], v[112:115], 0
	v_mfma_f32_16x16x32_bf16 v[222:225], v[16:19], v[120:123], 0
	v_mfma_f32_16x16x32_bf16 v[226:229], v[16:19], v[128:131], 0
	v_mfma_f32_16x16x32_bf16 v[230:233], v[16:19], v[136:139], 0
	v_mfma_f32_16x16x32_bf16 v[234:237], v[16:19], v[144:147], 0
	v_mfma_f32_16x16x32_bf16 v[238:241], v[16:19], v[152:155], 0
	v_mfma_f32_16x16x32_bf16 v[242:245], v[16:19], v[160:163], 0
	v_mfma_f32_16x16x32_bf16 v[252:255], v[16:19], v[168:171], 0
	v_mfma_f32_16x16x32_bf16 v[204:207], v[20:23], v[116:119], v[204:207]
	v_mfma_f32_16x16x32_bf16 v[222:225], v[20:23], v[124:127], v[222:225]
	v_mfma_f32_16x16x32_bf16 v[226:229], v[20:23], v[132:135], v[226:229]
	v_mfma_f32_16x16x32_bf16 v[230:233], v[20:23], v[140:143], v[230:233]
	v_mfma_f32_16x16x32_bf16 v[234:237], v[20:23], v[148:151], v[234:237]
	v_mfma_f32_16x16x32_bf16 v[238:241], v[20:23], v[156:159], v[238:241]
	v_mfma_f32_16x16x32_bf16 v[242:245], v[20:23], v[164:167], v[242:245]
	v_mfma_f32_16x16x32_bf16 v[252:255], v[20:23], v[172:175], v[252:255]
	v_lshl_add_u64 v[0:1], v[44:45], 0, s[48:49]
	v_lshl_add_u64 v[2:3], v[44:45], 0, s[50:51]
	v_lshl_add_u64 v[4:5], v[44:45], 0, s[52:53]
	v_lshl_add_u64 v[6:7], v[44:45], 0, s[54:55]
	v_lshl_add_u64 v[8:9], v[44:45], 0, s[56:57]
	v_lshl_add_u64 v[10:11], v[44:45], 0, s[58:59]
	v_lshl_add_u64 v[12:13], v[44:45], 0, s[60:61]
	v_lshl_add_u64 v[14:15], v[44:45], 0, s[62:63]
	global_load_dwordx4 v[112:115], v[0:1], off offset:128
	global_load_dwordx4 v[116:119], v[0:1], off offset:192
	global_load_dwordx4 v[120:123], v[2:3], off offset:128
	global_load_dwordx4 v[124:127], v[2:3], off offset:192
	global_load_dwordx4 v[128:131], v[4:5], off offset:128
	global_load_dwordx4 v[132:135], v[4:5], off offset:192
	global_load_dwordx4 v[136:139], v[6:7], off offset:128
	global_load_dwordx4 v[140:143], v[6:7], off offset:192
	global_load_dwordx4 v[144:147], v[8:9], off offset:128
	global_load_dwordx4 v[148:151], v[8:9], off offset:192
	global_load_dwordx4 v[152:155], v[10:11], off offset:128
	global_load_dwordx4 v[156:159], v[10:11], off offset:192
	global_load_dwordx4 v[160:163], v[12:13], off offset:128
	global_load_dwordx4 v[164:167], v[12:13], off offset:192
	global_load_dwordx4 v[168:171], v[14:15], off offset:128
	global_load_dwordx4 v[172:175], v[14:15], off offset:192
	s_waitcnt vmcnt(16)
	v_mfma_f32_16x16x32_bf16 v[32:35], v[24:27], v[48:51], v[32:35]
	v_mfma_f32_16x16x32_bf16 v[36:39], v[24:27], v[56:59], v[36:39]
	v_mfma_f32_16x16x32_bf16 v[180:183], v[24:27], v[64:67], v[180:183]
	v_mfma_f32_16x16x32_bf16 v[184:187], v[24:27], v[72:75], v[184:187]
	v_mfma_f32_16x16x32_bf16 v[188:191], v[24:27], v[80:83], v[188:191]
	v_mfma_f32_16x16x32_bf16 v[192:195], v[24:27], v[88:91], v[192:195]
	v_mfma_f32_16x16x32_bf16 v[196:199], v[24:27], v[96:99], v[196:199]
	v_mfma_f32_16x16x32_bf16 v[200:203], v[24:27], v[104:107], v[200:203]
	v_mfma_f32_16x16x32_bf16 v[32:35], v[28:31], v[52:55], v[32:35]
	v_mfma_f32_16x16x32_bf16 v[36:39], v[28:31], v[60:63], v[36:39]
	v_mfma_f32_16x16x32_bf16 v[180:183], v[28:31], v[68:71], v[180:183]
	v_mfma_f32_16x16x32_bf16 v[184:187], v[28:31], v[76:79], v[184:187]
	v_mfma_f32_16x16x32_bf16 v[188:191], v[28:31], v[84:87], v[188:191]
	v_mfma_f32_16x16x32_bf16 v[192:195], v[28:31], v[92:95], v[192:195]
	v_mfma_f32_16x16x32_bf16 v[196:199], v[28:31], v[100:103], v[196:199]
	v_mfma_f32_16x16x32_bf16 v[200:203], v[28:31], v[108:111], v[200:203]
	v_lshl_add_u64 v[2:3], v[44:45], 0, s[34:35]
	v_lshl_add_u64 v[4:5], v[44:45], 0, s[36:37]
	v_lshl_add_u64 v[6:7], v[44:45], 0, s[38:39]
	v_lshl_add_u64 v[8:9], v[44:45], 0, s[40:41]
	v_lshl_add_u64 v[10:11], v[44:45], 0, s[42:43]
	v_lshl_add_u64 v[12:13], v[44:45], 0, s[44:45]
	v_lshl_add_u64 v[14:15], v[44:45], 0, s[46:47]
	global_load_dwordx4 v[16:19], v[46:47], off offset:256
	global_load_dwordx4 v[20:23], v[46:47], off offset:320
	global_load_dwordx4 v[48:51], v[44:45], off offset:256
	global_load_dwordx4 v[52:55], v[44:45], off offset:320
	global_load_dwordx4 v[56:59], v[2:3], off offset:256
	global_load_dwordx4 v[60:63], v[2:3], off offset:320
	global_load_dwordx4 v[64:67], v[4:5], off offset:256
	global_load_dwordx4 v[68:71], v[4:5], off offset:320
	global_load_dwordx4 v[72:75], v[6:7], off offset:256
	global_load_dwordx4 v[76:79], v[6:7], off offset:320
	global_load_dwordx4 v[80:83], v[8:9], off offset:256
	global_load_dwordx4 v[84:87], v[8:9], off offset:320
	global_load_dwordx4 v[88:91], v[10:11], off offset:256
	global_load_dwordx4 v[92:95], v[10:11], off offset:320
	global_load_dwordx4 v[96:99], v[12:13], off offset:256
	global_load_dwordx4 v[100:103], v[12:13], off offset:320
	global_load_dwordx4 v[104:107], v[14:15], off offset:256
	global_load_dwordx4 v[108:111], v[14:15], off offset:320
	s_waitcnt vmcnt(18)
	v_mfma_f32_16x16x32_bf16 v[204:207], v[24:27], v[112:115], v[204:207]
	v_mfma_f32_16x16x32_bf16 v[222:225], v[24:27], v[120:123], v[222:225]
	v_mfma_f32_16x16x32_bf16 v[226:229], v[24:27], v[128:131], v[226:229]
	v_mfma_f32_16x16x32_bf16 v[230:233], v[24:27], v[136:139], v[230:233]
	v_mfma_f32_16x16x32_bf16 v[234:237], v[24:27], v[144:147], v[234:237]
	v_mfma_f32_16x16x32_bf16 v[238:241], v[24:27], v[152:155], v[238:241]
	v_mfma_f32_16x16x32_bf16 v[242:245], v[24:27], v[160:163], v[242:245]
	v_mfma_f32_16x16x32_bf16 v[252:255], v[24:27], v[168:171], v[252:255]
	v_mfma_f32_16x16x32_bf16 v[204:207], v[28:31], v[116:119], v[204:207]
	v_mfma_f32_16x16x32_bf16 v[222:225], v[28:31], v[124:127], v[222:225]
	v_mfma_f32_16x16x32_bf16 v[226:229], v[28:31], v[132:135], v[226:229]
	v_mfma_f32_16x16x32_bf16 v[230:233], v[28:31], v[140:143], v[230:233]
	v_mfma_f32_16x16x32_bf16 v[234:237], v[28:31], v[148:151], v[234:237]
	v_mfma_f32_16x16x32_bf16 v[238:241], v[28:31], v[156:159], v[238:241]
	v_mfma_f32_16x16x32_bf16 v[242:245], v[28:31], v[164:167], v[242:245]
	v_mfma_f32_16x16x32_bf16 v[252:255], v[28:31], v[172:175], v[252:255]
	v_lshl_add_u64 v[0:1], v[44:45], 0, s[48:49]
	v_lshl_add_u64 v[2:3], v[44:45], 0, s[50:51]
	v_lshl_add_u64 v[4:5], v[44:45], 0, s[52:53]
	v_lshl_add_u64 v[6:7], v[44:45], 0, s[54:55]
	v_lshl_add_u64 v[8:9], v[44:45], 0, s[56:57]
	v_lshl_add_u64 v[10:11], v[44:45], 0, s[58:59]
	v_lshl_add_u64 v[12:13], v[44:45], 0, s[60:61]
	v_lshl_add_u64 v[14:15], v[44:45], 0, s[62:63]
	global_load_dwordx4 v[112:115], v[0:1], off offset:256
	global_load_dwordx4 v[116:119], v[0:1], off offset:320
	global_load_dwordx4 v[120:123], v[2:3], off offset:256
	global_load_dwordx4 v[124:127], v[2:3], off offset:320
	global_load_dwordx4 v[128:131], v[4:5], off offset:256
	global_load_dwordx4 v[132:135], v[4:5], off offset:320
	global_load_dwordx4 v[136:139], v[6:7], off offset:256
	global_load_dwordx4 v[140:143], v[6:7], off offset:320
	global_load_dwordx4 v[144:147], v[8:9], off offset:256
	global_load_dwordx4 v[148:151], v[8:9], off offset:320
	global_load_dwordx4 v[152:155], v[10:11], off offset:256
	global_load_dwordx4 v[156:159], v[10:11], off offset:320
	global_load_dwordx4 v[160:163], v[12:13], off offset:256
	global_load_dwordx4 v[164:167], v[12:13], off offset:320
	global_load_dwordx4 v[168:171], v[14:15], off offset:256
	global_load_dwordx4 v[172:175], v[14:15], off offset:320
	s_waitcnt vmcnt(16)
	v_mfma_f32_16x16x32_bf16 v[32:35], v[16:19], v[48:51], v[32:35]
	v_mfma_f32_16x16x32_bf16 v[36:39], v[16:19], v[56:59], v[36:39]
	v_mfma_f32_16x16x32_bf16 v[180:183], v[16:19], v[64:67], v[180:183]
	v_mfma_f32_16x16x32_bf16 v[184:187], v[16:19], v[72:75], v[184:187]
	v_mfma_f32_16x16x32_bf16 v[188:191], v[16:19], v[80:83], v[188:191]
	v_mfma_f32_16x16x32_bf16 v[192:195], v[16:19], v[88:91], v[192:195]
	v_mfma_f32_16x16x32_bf16 v[196:199], v[16:19], v[96:99], v[196:199]
	v_mfma_f32_16x16x32_bf16 v[200:203], v[16:19], v[104:107], v[200:203]
	v_mfma_f32_16x16x32_bf16 v[32:35], v[20:23], v[52:55], v[32:35]
	v_mfma_f32_16x16x32_bf16 v[36:39], v[20:23], v[60:63], v[36:39]
	v_mfma_f32_16x16x32_bf16 v[180:183], v[20:23], v[68:71], v[180:183]
	v_mfma_f32_16x16x32_bf16 v[184:187], v[20:23], v[76:79], v[184:187]
	v_mfma_f32_16x16x32_bf16 v[188:191], v[20:23], v[84:87], v[188:191]
	v_mfma_f32_16x16x32_bf16 v[192:195], v[20:23], v[92:95], v[192:195]
	v_mfma_f32_16x16x32_bf16 v[196:199], v[20:23], v[100:103], v[196:199]
	v_mfma_f32_16x16x32_bf16 v[200:203], v[20:23], v[108:111], v[200:203]
	v_lshl_add_u64 v[2:3], v[44:45], 0, s[34:35]
	v_lshl_add_u64 v[4:5], v[44:45], 0, s[36:37]
	v_lshl_add_u64 v[6:7], v[44:45], 0, s[38:39]
	v_lshl_add_u64 v[8:9], v[44:45], 0, s[40:41]
	v_lshl_add_u64 v[10:11], v[44:45], 0, s[42:43]
	v_lshl_add_u64 v[12:13], v[44:45], 0, s[44:45]
	v_lshl_add_u64 v[14:15], v[44:45], 0, s[46:47]
	global_load_dwordx4 v[24:27], v[46:47], off offset:384
	global_load_dwordx4 v[28:31], v[46:47], off offset:448
	global_load_dwordx4 v[48:51], v[44:45], off offset:384
	global_load_dwordx4 v[52:55], v[44:45], off offset:448
	global_load_dwordx4 v[56:59], v[2:3], off offset:384
	global_load_dwordx4 v[60:63], v[2:3], off offset:448
	global_load_dwordx4 v[64:67], v[4:5], off offset:384
	global_load_dwordx4 v[68:71], v[4:5], off offset:448
	global_load_dwordx4 v[72:75], v[6:7], off offset:384
	global_load_dwordx4 v[76:79], v[6:7], off offset:448
	global_load_dwordx4 v[80:83], v[8:9], off offset:384
	global_load_dwordx4 v[84:87], v[8:9], off offset:448
	global_load_dwordx4 v[88:91], v[10:11], off offset:384
	global_load_dwordx4 v[92:95], v[10:11], off offset:448
	global_load_dwordx4 v[96:99], v[12:13], off offset:384
	global_load_dwordx4 v[100:103], v[12:13], off offset:448
	global_load_dwordx4 v[104:107], v[14:15], off offset:384
	global_load_dwordx4 v[108:111], v[14:15], off offset:448
	s_waitcnt vmcnt(18)
	v_mfma_f32_16x16x32_bf16 v[204:207], v[16:19], v[112:115], v[204:207]
	v_mfma_f32_16x16x32_bf16 v[222:225], v[16:19], v[120:123], v[222:225]
	v_mfma_f32_16x16x32_bf16 v[226:229], v[16:19], v[128:131], v[226:229]
	v_mfma_f32_16x16x32_bf16 v[230:233], v[16:19], v[136:139], v[230:233]
	v_mfma_f32_16x16x32_bf16 v[234:237], v[16:19], v[144:147], v[234:237]
	v_mfma_f32_16x16x32_bf16 v[238:241], v[16:19], v[152:155], v[238:241]
	v_mfma_f32_16x16x32_bf16 v[242:245], v[16:19], v[160:163], v[242:245]
	v_mfma_f32_16x16x32_bf16 v[252:255], v[16:19], v[168:171], v[252:255]
	v_mfma_f32_16x16x32_bf16 v[204:207], v[20:23], v[116:119], v[204:207]
	v_mfma_f32_16x16x32_bf16 v[222:225], v[20:23], v[124:127], v[222:225]
	v_mfma_f32_16x16x32_bf16 v[226:229], v[20:23], v[132:135], v[226:229]
	v_mfma_f32_16x16x32_bf16 v[230:233], v[20:23], v[140:143], v[230:233]
	v_mfma_f32_16x16x32_bf16 v[234:237], v[20:23], v[148:151], v[234:237]
	v_mfma_f32_16x16x32_bf16 v[238:241], v[20:23], v[156:159], v[238:241]
	v_mfma_f32_16x16x32_bf16 v[242:245], v[20:23], v[164:167], v[242:245]
	v_mfma_f32_16x16x32_bf16 v[252:255], v[20:23], v[172:175], v[252:255]
	v_lshl_add_u64 v[0:1], v[44:45], 0, s[48:49]
	v_lshl_add_u64 v[2:3], v[44:45], 0, s[50:51]
	v_lshl_add_u64 v[4:5], v[44:45], 0, s[52:53]
	v_lshl_add_u64 v[6:7], v[44:45], 0, s[54:55]
	v_lshl_add_u64 v[8:9], v[44:45], 0, s[56:57]
	v_lshl_add_u64 v[10:11], v[44:45], 0, s[58:59]
	v_lshl_add_u64 v[12:13], v[44:45], 0, s[60:61]
	v_lshl_add_u64 v[14:15], v[44:45], 0, s[62:63]
	global_load_dwordx4 v[112:115], v[0:1], off offset:384
	global_load_dwordx4 v[116:119], v[0:1], off offset:448
	global_load_dwordx4 v[120:123], v[2:3], off offset:384
	global_load_dwordx4 v[124:127], v[2:3], off offset:448
	global_load_dwordx4 v[128:131], v[4:5], off offset:384
	global_load_dwordx4 v[132:135], v[4:5], off offset:448
	global_load_dwordx4 v[136:139], v[6:7], off offset:384
	global_load_dwordx4 v[140:143], v[6:7], off offset:448
	global_load_dwordx4 v[144:147], v[8:9], off offset:384
	global_load_dwordx4 v[148:151], v[8:9], off offset:448
	global_load_dwordx4 v[152:155], v[10:11], off offset:384
	global_load_dwordx4 v[156:159], v[10:11], off offset:448
	global_load_dwordx4 v[160:163], v[12:13], off offset:384
	global_load_dwordx4 v[164:167], v[12:13], off offset:448
	global_load_dwordx4 v[168:171], v[14:15], off offset:384
	global_load_dwordx4 v[172:175], v[14:15], off offset:448
	s_waitcnt vmcnt(16)
	v_mfma_f32_16x16x32_bf16 v[32:35], v[24:27], v[48:51], v[32:35]
	v_mfma_f32_16x16x32_bf16 v[36:39], v[24:27], v[56:59], v[36:39]
	v_mfma_f32_16x16x32_bf16 v[180:183], v[24:27], v[64:67], v[180:183]
	v_mfma_f32_16x16x32_bf16 v[184:187], v[24:27], v[72:75], v[184:187]
	v_mfma_f32_16x16x32_bf16 v[188:191], v[24:27], v[80:83], v[188:191]
	v_mfma_f32_16x16x32_bf16 v[192:195], v[24:27], v[88:91], v[192:195]
	v_mfma_f32_16x16x32_bf16 v[196:199], v[24:27], v[96:99], v[196:199]
	v_mfma_f32_16x16x32_bf16 v[200:203], v[24:27], v[104:107], v[200:203]
	v_mfma_f32_16x16x32_bf16 v[32:35], v[28:31], v[52:55], v[32:35]
	v_mfma_f32_16x16x32_bf16 v[36:39], v[28:31], v[60:63], v[36:39]
	v_mfma_f32_16x16x32_bf16 v[180:183], v[28:31], v[68:71], v[180:183]
	v_mfma_f32_16x16x32_bf16 v[184:187], v[28:31], v[76:79], v[184:187]
	v_mfma_f32_16x16x32_bf16 v[188:191], v[28:31], v[84:87], v[188:191]
	v_mfma_f32_16x16x32_bf16 v[192:195], v[28:31], v[92:95], v[192:195]
	v_mfma_f32_16x16x32_bf16 v[196:199], v[28:31], v[100:103], v[196:199]
	v_mfma_f32_16x16x32_bf16 v[200:203], v[28:31], v[108:111], v[200:203]
	v_lshl_add_u64 v[2:3], v[44:45], 0, s[34:35]
	v_lshl_add_u64 v[4:5], v[44:45], 0, s[36:37]
	v_lshl_add_u64 v[6:7], v[44:45], 0, s[38:39]
	v_lshl_add_u64 v[8:9], v[44:45], 0, s[40:41]
	v_lshl_add_u64 v[10:11], v[44:45], 0, s[42:43]
	v_lshl_add_u64 v[12:13], v[44:45], 0, s[44:45]
	v_lshl_add_u64 v[14:15], v[44:45], 0, s[46:47]
	global_load_dwordx4 v[16:19], v[46:47], off offset:512
	global_load_dwordx4 v[20:23], v[46:47], off offset:576
	global_load_dwordx4 v[48:51], v[44:45], off offset:512
	global_load_dwordx4 v[52:55], v[44:45], off offset:576
	global_load_dwordx4 v[56:59], v[2:3], off offset:512
	global_load_dwordx4 v[60:63], v[2:3], off offset:576
	global_load_dwordx4 v[64:67], v[4:5], off offset:512
	global_load_dwordx4 v[68:71], v[4:5], off offset:576
	global_load_dwordx4 v[72:75], v[6:7], off offset:512
	global_load_dwordx4 v[76:79], v[6:7], off offset:576
	global_load_dwordx4 v[80:83], v[8:9], off offset:512
	global_load_dwordx4 v[84:87], v[8:9], off offset:576
	global_load_dwordx4 v[88:91], v[10:11], off offset:512
	global_load_dwordx4 v[92:95], v[10:11], off offset:576
	global_load_dwordx4 v[96:99], v[12:13], off offset:512
	global_load_dwordx4 v[100:103], v[12:13], off offset:576
	global_load_dwordx4 v[104:107], v[14:15], off offset:512
	global_load_dwordx4 v[108:111], v[14:15], off offset:576
	s_waitcnt vmcnt(18)
	v_mfma_f32_16x16x32_bf16 v[204:207], v[24:27], v[112:115], v[204:207]
	v_mfma_f32_16x16x32_bf16 v[222:225], v[24:27], v[120:123], v[222:225]
	v_mfma_f32_16x16x32_bf16 v[226:229], v[24:27], v[128:131], v[226:229]
	v_mfma_f32_16x16x32_bf16 v[230:233], v[24:27], v[136:139], v[230:233]
	v_mfma_f32_16x16x32_bf16 v[234:237], v[24:27], v[144:147], v[234:237]
	v_mfma_f32_16x16x32_bf16 v[238:241], v[24:27], v[152:155], v[238:241]
	v_mfma_f32_16x16x32_bf16 v[242:245], v[24:27], v[160:163], v[242:245]
	v_mfma_f32_16x16x32_bf16 v[252:255], v[24:27], v[168:171], v[252:255]
	v_mfma_f32_16x16x32_bf16 v[204:207], v[28:31], v[116:119], v[204:207]
	v_mfma_f32_16x16x32_bf16 v[222:225], v[28:31], v[124:127], v[222:225]
	v_mfma_f32_16x16x32_bf16 v[226:229], v[28:31], v[132:135], v[226:229]
	v_mfma_f32_16x16x32_bf16 v[230:233], v[28:31], v[140:143], v[230:233]
	v_mfma_f32_16x16x32_bf16 v[234:237], v[28:31], v[148:151], v[234:237]
	v_mfma_f32_16x16x32_bf16 v[238:241], v[28:31], v[156:159], v[238:241]
	v_mfma_f32_16x16x32_bf16 v[242:245], v[28:31], v[164:167], v[242:245]
	v_mfma_f32_16x16x32_bf16 v[252:255], v[28:31], v[172:175], v[252:255]
	v_lshl_add_u64 v[0:1], v[44:45], 0, s[48:49]
	v_lshl_add_u64 v[2:3], v[44:45], 0, s[50:51]
	v_lshl_add_u64 v[4:5], v[44:45], 0, s[52:53]
	v_lshl_add_u64 v[6:7], v[44:45], 0, s[54:55]
	v_lshl_add_u64 v[8:9], v[44:45], 0, s[56:57]
	v_lshl_add_u64 v[10:11], v[44:45], 0, s[58:59]
	v_lshl_add_u64 v[12:13], v[44:45], 0, s[60:61]
	v_lshl_add_u64 v[14:15], v[44:45], 0, s[62:63]
	global_load_dwordx4 v[112:115], v[0:1], off offset:512
	global_load_dwordx4 v[116:119], v[0:1], off offset:576
	global_load_dwordx4 v[120:123], v[2:3], off offset:512
	global_load_dwordx4 v[124:127], v[2:3], off offset:576
	global_load_dwordx4 v[128:131], v[4:5], off offset:512
	global_load_dwordx4 v[132:135], v[4:5], off offset:576
	global_load_dwordx4 v[136:139], v[6:7], off offset:512
	global_load_dwordx4 v[140:143], v[6:7], off offset:576
	global_load_dwordx4 v[144:147], v[8:9], off offset:512
	global_load_dwordx4 v[148:151], v[8:9], off offset:576
	global_load_dwordx4 v[152:155], v[10:11], off offset:512
	global_load_dwordx4 v[156:159], v[10:11], off offset:576
	global_load_dwordx4 v[160:163], v[12:13], off offset:512
	global_load_dwordx4 v[164:167], v[12:13], off offset:576
	global_load_dwordx4 v[168:171], v[14:15], off offset:512
	global_load_dwordx4 v[172:175], v[14:15], off offset:576
	s_waitcnt vmcnt(16)
	v_mfma_f32_16x16x32_bf16 v[32:35], v[16:19], v[48:51], v[32:35]
	v_mfma_f32_16x16x32_bf16 v[36:39], v[16:19], v[56:59], v[36:39]
	v_mfma_f32_16x16x32_bf16 v[180:183], v[16:19], v[64:67], v[180:183]
	v_mfma_f32_16x16x32_bf16 v[184:187], v[16:19], v[72:75], v[184:187]
	v_mfma_f32_16x16x32_bf16 v[188:191], v[16:19], v[80:83], v[188:191]
	v_mfma_f32_16x16x32_bf16 v[192:195], v[16:19], v[88:91], v[192:195]
	v_mfma_f32_16x16x32_bf16 v[196:199], v[16:19], v[96:99], v[196:199]
	v_mfma_f32_16x16x32_bf16 v[200:203], v[16:19], v[104:107], v[200:203]
	v_mfma_f32_16x16x32_bf16 v[32:35], v[20:23], v[52:55], v[32:35]
	v_mfma_f32_16x16x32_bf16 v[36:39], v[20:23], v[60:63], v[36:39]
	v_mfma_f32_16x16x32_bf16 v[180:183], v[20:23], v[68:71], v[180:183]
	v_mfma_f32_16x16x32_bf16 v[184:187], v[20:23], v[76:79], v[184:187]
	v_mfma_f32_16x16x32_bf16 v[188:191], v[20:23], v[84:87], v[188:191]
	v_mfma_f32_16x16x32_bf16 v[192:195], v[20:23], v[92:95], v[192:195]
	v_mfma_f32_16x16x32_bf16 v[196:199], v[20:23], v[100:103], v[196:199]
	v_mfma_f32_16x16x32_bf16 v[200:203], v[20:23], v[108:111], v[200:203]
	v_lshl_add_u64 v[2:3], v[44:45], 0, s[34:35]
	v_lshl_add_u64 v[4:5], v[44:45], 0, s[36:37]
	v_lshl_add_u64 v[6:7], v[44:45], 0, s[38:39]
	v_lshl_add_u64 v[8:9], v[44:45], 0, s[40:41]
	v_lshl_add_u64 v[10:11], v[44:45], 0, s[42:43]
	v_lshl_add_u64 v[12:13], v[44:45], 0, s[44:45]
	v_lshl_add_u64 v[14:15], v[44:45], 0, s[46:47]
	global_load_dwordx4 v[24:27], v[46:47], off offset:640
	global_load_dwordx4 v[48:51], v[44:45], off offset:640
	global_load_dwordx4 v[56:59], v[2:3], off offset:640
	global_load_dwordx4 v[64:67], v[4:5], off offset:640
	global_load_dwordx4 v[72:75], v[6:7], off offset:640
	global_load_dwordx4 v[80:83], v[8:9], off offset:640
	global_load_dwordx4 v[88:91], v[10:11], off offset:640
	global_load_dwordx4 v[96:99], v[12:13], off offset:640
	global_load_dwordx4 v[104:107], v[14:15], off offset:640
	s_waitcnt vmcnt(9)
	v_mfma_f32_16x16x32_bf16 v[204:207], v[16:19], v[112:115], v[204:207]
	v_mfma_f32_16x16x32_bf16 v[222:225], v[16:19], v[120:123], v[222:225]
	v_mfma_f32_16x16x32_bf16 v[226:229], v[16:19], v[128:131], v[226:229]
	v_mfma_f32_16x16x32_bf16 v[230:233], v[16:19], v[136:139], v[230:233]
	v_mfma_f32_16x16x32_bf16 v[234:237], v[16:19], v[144:147], v[234:237]
	v_mfma_f32_16x16x32_bf16 v[238:241], v[16:19], v[152:155], v[238:241]
	v_mfma_f32_16x16x32_bf16 v[242:245], v[16:19], v[160:163], v[242:245]
	v_mfma_f32_16x16x32_bf16 v[252:255], v[16:19], v[168:171], v[252:255]
	v_mfma_f32_16x16x32_bf16 v[204:207], v[20:23], v[116:119], v[204:207]
	v_mfma_f32_16x16x32_bf16 v[222:225], v[20:23], v[124:127], v[222:225]
	v_mfma_f32_16x16x32_bf16 v[226:229], v[20:23], v[132:135], v[226:229]
	v_mfma_f32_16x16x32_bf16 v[230:233], v[20:23], v[140:143], v[230:233]
	v_mfma_f32_16x16x32_bf16 v[234:237], v[20:23], v[148:151], v[234:237]
	v_mfma_f32_16x16x32_bf16 v[238:241], v[20:23], v[156:159], v[238:241]
	v_mfma_f32_16x16x32_bf16 v[242:245], v[20:23], v[164:167], v[242:245]
	v_mfma_f32_16x16x32_bf16 v[252:255], v[20:23], v[172:175], v[252:255]
	v_lshl_add_u64 v[0:1], v[44:45], 0, s[48:49]
	v_lshl_add_u64 v[2:3], v[44:45], 0, s[50:51]
	v_lshl_add_u64 v[4:5], v[44:45], 0, s[52:53]
	v_lshl_add_u64 v[6:7], v[44:45], 0, s[54:55]
	v_lshl_add_u64 v[8:9], v[44:45], 0, s[56:57]
	v_lshl_add_u64 v[10:11], v[44:45], 0, s[58:59]
	v_lshl_add_u64 v[12:13], v[44:45], 0, s[60:61]
	v_lshl_add_u64 v[14:15], v[44:45], 0, s[62:63]
	global_load_dwordx4 v[112:115], v[0:1], off offset:640
	global_load_dwordx4 v[120:123], v[2:3], off offset:640
	global_load_dwordx4 v[128:131], v[4:5], off offset:640
	global_load_dwordx4 v[136:139], v[6:7], off offset:640
	global_load_dwordx4 v[144:147], v[8:9], off offset:640
	global_load_dwordx4 v[152:155], v[10:11], off offset:640
	global_load_dwordx4 v[160:163], v[12:13], off offset:640
	global_load_dwordx4 v[168:171], v[14:15], off offset:640
	s_waitcnt vmcnt(8)
	v_mfma_f32_16x16x32_bf16 v[32:35], v[24:27], v[48:51], v[32:35]
	v_mfma_f32_16x16x32_bf16 v[36:39], v[24:27], v[56:59], v[36:39]
	v_mfma_f32_16x16x32_bf16 v[180:183], v[24:27], v[64:67], v[180:183]
	v_mfma_f32_16x16x32_bf16 v[184:187], v[24:27], v[72:75], v[184:187]
	v_mfma_f32_16x16x32_bf16 v[188:191], v[24:27], v[80:83], v[188:191]
	v_mfma_f32_16x16x32_bf16 v[192:195], v[24:27], v[88:91], v[192:195]
	v_mfma_f32_16x16x32_bf16 v[196:199], v[24:27], v[96:99], v[196:199]
	v_mfma_f32_16x16x32_bf16 v[200:203], v[24:27], v[104:107], v[200:203]
	s_waitcnt vmcnt(0)
	v_mfma_f32_16x16x32_bf16 v[204:207], v[24:27], v[112:115], v[204:207]
	v_mfma_f32_16x16x32_bf16 v[222:225], v[24:27], v[120:123], v[222:225]
	v_mfma_f32_16x16x32_bf16 v[226:229], v[24:27], v[128:131], v[226:229]
	v_mfma_f32_16x16x32_bf16 v[230:233], v[24:27], v[136:139], v[230:233]
	v_mfma_f32_16x16x32_bf16 v[234:237], v[24:27], v[144:147], v[234:237]
	v_mfma_f32_16x16x32_bf16 v[238:241], v[24:27], v[152:155], v[238:241]
	v_mfma_f32_16x16x32_bf16 v[242:245], v[24:27], v[160:163], v[242:245]
	v_mfma_f32_16x16x32_bf16 v[252:255], v[24:27], v[168:171], v[252:255]
	v_add_u32_e32 v78, s23, v211
	v_ashrrev_i32_e32 v79, 31, v78
	v_lshlrev_b64 v[82:83], 1, v[78:79]
	v_or_b32_e32 v44, s24, v210
	v_ashrrev_i32_e32 v45, 31, v44
	v_or_b32_e32 v84, 1, v44
	v_ashrrev_i32_e32 v85, 31, v84
	s_barrier
	v_or_b32_e32 v86, 2, v44
	v_or_b32_e32 v88, 3, v44
	v_lshlrev_b64 v[44:45], 11, v[44:45]
	v_ashrrev_i32_e32 v87, 31, v86
	v_ashrrev_i32_e32 v89, 31, v88
	v_lshl_add_u64 v[44:45], s[16:17], 0, v[44:45]
	v_lshlrev_b64 v[70:71], 11, v[84:85]
	v_lshlrev_b64 v[72:73], 11, v[86:87]
	v_lshlrev_b64 v[84:85], 11, v[88:89]
	v_lshl_add_u64 v[86:87], v[44:45], 0, v[82:83]
	v_lshl_add_u64 v[44:45], s[16:17], 0, v[70:71]
	v_lshl_add_u64 v[70:71], s[16:17], 0, v[72:73]
	v_lshl_add_u64 v[72:73], s[16:17], 0, v[84:85]
	v_lshl_add_u64 v[84:85], v[44:45], 0, v[82:83]
	v_lshl_add_u64 v[70:71], v[70:71], 0, v[82:83]
	v_lshl_add_u64 v[72:73], v[72:73], 0, v[82:83]
	ds_write_b128 v220, v[32:35]
	ds_write_b128 v220, v[36:39] offset:1024
	ds_write_b128 v220, v[180:183] offset:2048
	ds_write_b128 v220, v[184:187] offset:3072
	ds_write_b128 v220, v[188:191] offset:4096
	ds_write_b128 v220, v[192:195] offset:5120
	ds_write_b128 v220, v[196:199] offset:6144
	ds_write_b128 v220, v[200:203] offset:7168
	ds_write_b128 v220, v[204:207] offset:8192
	ds_write_b128 v220, v[222:225] offset:9216
	ds_write_b128 v220, v[226:229] offset:10240
	ds_write_b128 v220, v[230:233] offset:11264
	ds_write_b128 v220, v[234:237] offset:12288
	ds_write_b128 v220, v[238:241] offset:13312
	ds_write_b128 v220, v[242:245] offset:14336
	ds_write_b128 v220, v[252:255] offset:15360
	s_waitcnt lgkmcnt(0)
	s_barrier
	global_load_ushort v68, v[86:87], off
	global_load_ushort v69, v[86:87], off offset:32
	global_load_ushort v74, v[84:85], off
	global_load_ushort v75, v[84:85], off offset:32
	global_load_ushort v76, v[70:71], off
	global_load_ushort v77, v[70:71], off offset:32
	global_load_ushort v78, v[72:73], off
	global_load_ushort v79, v[72:73], off offset:32
	ds_read_b128 v[0:3], v177
	ds_read_b128 v[4:7], v177 offset:1024
	ds_read_b128 v[8:11], v177 offset:16384
	ds_read_b128 v[12:15], v177 offset:17408
	ds_read_b128 v[16:19], v177 offset:32768
	ds_read_b128 v[20:23], v177 offset:33792
	ds_read_b128 v[24:27], v177 offset:49152
	ds_read_b128 v[28:31], v177 offset:50176
	ds_read_b128 v[32:35], v212
	ds_read_b128 v[36:39], v213
	ds_read_b128 v[44:47], v214
	ds_read_b128 v[48:51], v215
	ds_read_b128 v[52:55], v216
	ds_read_b128 v[56:59], v217
	ds_read_b128 v[60:63], v218
	ds_read_b128 v[64:67], v219
	s_waitcnt lgkmcnt(14)
	v_pk_add_f32 v[0:1], v[0:1], 0 op_sel_hi:[1,0]
	v_pk_add_f32 v[2:3], v[2:3], 0 op_sel_hi:[1,0]
	v_pk_add_f32 v[6:7], v[6:7], 0 op_sel_hi:[1,0]
	v_pk_add_f32 v[4:5], v[4:5], 0 op_sel_hi:[1,0]
	s_waitcnt lgkmcnt(13)
	v_pk_add_f32 v[0:1], v[0:1], v[8:9]
	v_pk_add_f32 v[2:3], v[2:3], v[10:11]
	s_waitcnt lgkmcnt(12)
	v_pk_add_f32 v[6:7], v[6:7], v[14:15]
	v_pk_add_f32 v[4:5], v[4:5], v[12:13]
	s_waitcnt lgkmcnt(11)
	v_pk_add_f32 v[0:1], v[0:1], v[16:17]
	v_pk_add_f32 v[2:3], v[2:3], v[18:19]
	s_waitcnt lgkmcnt(10)
	v_pk_add_f32 v[6:7], v[6:7], v[22:23]
	v_pk_add_f32 v[4:5], v[4:5], v[20:21]
	s_waitcnt lgkmcnt(9)
	v_pk_add_f32 v[0:1], v[0:1], v[24:25]
	v_pk_add_f32 v[2:3], v[2:3], v[26:27]
	s_waitcnt lgkmcnt(8)
	v_pk_add_f32 v[6:7], v[6:7], v[30:31]
	v_pk_add_f32 v[4:5], v[4:5], v[28:29]
	s_waitcnt lgkmcnt(7)
	v_pk_add_f32 v[0:1], v[0:1], v[32:33]
	v_pk_add_f32 v[2:3], v[2:3], v[34:35]
	s_waitcnt lgkmcnt(6)
	v_pk_add_f32 v[6:7], v[6:7], v[38:39]
	v_pk_add_f32 v[4:5], v[4:5], v[36:37]
	s_waitcnt lgkmcnt(5)
	v_pk_add_f32 v[0:1], v[0:1], v[44:45]
	v_pk_add_f32 v[2:3], v[2:3], v[46:47]
	s_waitcnt lgkmcnt(4)
	v_pk_add_f32 v[6:7], v[6:7], v[50:51]
	v_pk_add_f32 v[4:5], v[4:5], v[48:49]
	s_waitcnt lgkmcnt(3)
	v_pk_add_f32 v[0:1], v[0:1], v[52:53]
	v_pk_add_f32 v[2:3], v[2:3], v[54:55]
	s_waitcnt lgkmcnt(2)
	v_pk_add_f32 v[6:7], v[6:7], v[58:59]
	v_pk_add_f32 v[4:5], v[4:5], v[56:57]
	s_waitcnt lgkmcnt(1)
	v_pk_add_f32 v[0:1], v[0:1], v[60:61]
	v_pk_add_f32 v[2:3], v[2:3], v[62:63]
	s_waitcnt lgkmcnt(0)
	v_pk_add_f32 v[6:7], v[6:7], v[66:67]
	v_pk_add_f32 v[4:5], v[4:5], v[64:65]
	s_waitcnt vmcnt(7)
	v_lshlrev_b32_e32 v8, 16, v68
	s_waitcnt vmcnt(6)
	v_lshlrev_b32_e32 v9, 16, v69
	s_waitcnt vmcnt(5)
	v_lshlrev_b32_e32 v10, 16, v74
	s_waitcnt vmcnt(4)
	v_lshlrev_b32_e32 v11, 16, v75
	s_waitcnt vmcnt(3)
	v_lshlrev_b32_e32 v12, 16, v76
	s_waitcnt vmcnt(2)
	v_lshlrev_b32_e32 v13, 16, v77
	s_waitcnt vmcnt(1)
	v_lshlrev_b32_e32 v14, 16, v78
	s_waitcnt vmcnt(0)
	v_lshlrev_b32_e32 v15, 16, v79
	v_add_f32_e32 v0, v0, v8
	v_add_f32_e32 v4, v4, v9
	v_add_f32_e32 v1, v1, v10
	v_add_f32_e32 v5, v5, v11
	v_add_f32_e32 v2, v2, v12
	v_add_f32_e32 v6, v6, v13
	v_add_f32_e32 v3, v3, v14
	v_add_f32_e32 v7, v7, v15
	v_bfe_u32 v8, v0, 16, 1
	v_bfe_u32 v9, v4, 16, 1
	v_bfe_u32 v10, v1, 16, 1
	v_bfe_u32 v11, v5, 16, 1
	v_bfe_u32 v12, v2, 16, 1
	v_bfe_u32 v13, v6, 16, 1
	v_bfe_u32 v14, v3, 16, 1
	v_bfe_u32 v15, v7, 16, 1
	v_add3_u32 v0, v0, v8, s22
	v_add3_u32 v4, v4, v9, s22
	v_add3_u32 v1, v1, v10, s22
	v_add3_u32 v5, v5, v11, s22
	v_add3_u32 v2, v2, v12, s22
	v_add3_u32 v6, v6, v13, s22
	v_add3_u32 v3, v3, v14, s22
	v_add3_u32 v7, v7, v15, s22
	global_store_short_d16_hi v[86:87], v0, off
	global_store_short_d16_hi v[86:87], v4, off offset:32
	global_store_short_d16_hi v[84:85], v1, off
	global_store_short_d16_hi v[84:85], v5, off offset:32
	global_store_short_d16_hi v[70:71], v2, off
	global_store_short_d16_hi v[70:71], v6, off offset:32
	global_store_short_d16_hi v[72:73], v3, off
	global_store_short_d16_hi v[72:73], v7, off offset:32
	s_cbranch_scc1 .LBB0_1488

.LBB0_1507:
	s_or_b64 exec, exec, s[8:9]
	v_cvt_f32_u32_e32 v4, v2
	s_waitcnt vmcnt(0)
	v_readfirstlane_b32 s6, v3
	v_sub_u32_e32 v3, 0, v2
	v_rcp_iflag_f32_e32 v4, v4
	v_add_u32_e32 v5, s6, v1
	v_mul_f32_e32 v4, 0x4f7ffffe, v4
	v_cvt_u32_f32_e32 v4, v4
	v_mul_lo_u32 v1, v3, v4
	v_mul_hi_u32 v1, v4, v1
	v_add_u32_e32 v1, v4, v1
	v_mul_hi_u32 v1, v5, v1
	v_mul_lo_u32 v3, v1, v2
	v_sub_u32_e32 v3, v5, v3
	v_add_u32_e32 v4, 1, v1
	v_cmp_ge_u32_e32 vcc, v3, v2
	s_nop 1
	v_cndmask_b32_e32 v1, v1, v4, vcc
	v_sub_u32_e32 v4, v3, v2
	v_cndmask_b32_e32 v3, v3, v4, vcc
	v_add_u32_e32 v4, 1, v1
	v_cmp_ge_u32_e32 vcc, v3, v2
	v_add_u32_e32 v3, 1, v5
	s_nop 0
	v_cndmask_b32_e32 v1, v1, v4, vcc
	v_mul_lo_u32 v4, v2, v1
	v_add_u32_e32 v2, v4, v2
	v_cmp_ne_u32_e32 vcc, v3, v2
	s_and_saveexec_b64 s[6:7], vcc
	s_xor_b64 s[6:7], exec, s[6:7]
	s_cbranch_execz .LBB0_1521
	s_waitcnt lgkmcnt(0)
	buffer_inv sc1
	v_mov_b32_e32 v0, 0x2000
	global_load_dword v0, v0, s[2:3] offset:1024 sc1
	s_add_u32 s12, s2, 0x2400
	s_addc_u32 s13, s3, 0
	s_waitcnt vmcnt(0)
	v_cmp_eq_u32_e32 vcc, v0, v1
	s_and_saveexec_b64 s[8:9], vcc
	s_cbranch_execz .LBB0_1520
	s_add_u32 s10, s92, 0x80200
	s_addc_u32 s11, s93, 0
	s_mov_b32 s26, 1
	s_mov_b64 s[14:15], 0
	v_mov_b32_e32 v0, 0
	s_branch .LBB0_1511

	.amdhsa_kernel _Z14fwd_megakernel4Args
		.amdhsa_group_segment_fixed_size 0
		.amdhsa_private_segment_fixed_size 0
		.amdhsa_kernarg_size 520
		.amdhsa_user_sgpr_count 2
		.amdhsa_user_sgpr_dispatch_ptr 0
		.amdhsa_user_sgpr_queue_ptr 0
		.amdhsa_user_sgpr_kernarg_segment_ptr 1
		.amdhsa_user_sgpr_dispatch_id 0
		.amdhsa_user_sgpr_kernarg_preload_length 0
		.amdhsa_user_sgpr_kernarg_preload_offset 0
		.amdhsa_user_sgpr_private_segment_size 0
		.amdhsa_uses_dynamic_stack 0
		.amdhsa_enable_private_segment 0
		.amdhsa_system_sgpr_workgroup_id_x 1
		.amdhsa_system_sgpr_workgroup_id_y 0
		.amdhsa_system_sgpr_workgroup_id_z 0
		.amdhsa_system_sgpr_workgroup_info 0
		.amdhsa_system_vgpr_workitem_id 2
		.amdhsa_next_free_vgpr 256
		.amdhsa_next_free_sgpr 100
		.amdhsa_accum_offset 256
		.amdhsa_reserve_vcc 1
		.amdhsa_float_round_mode_32 0
		.amdhsa_float_round_mode_16_64 0
		.amdhsa_float_denorm_mode_32 3
		.amdhsa_float_denorm_mode_16_64 3
		.amdhsa_dx10_clamp 1
		.amdhsa_ieee_mode 1
		.amdhsa_fp16_overflow 0
		.amdhsa_tg_split 0
		.amdhsa_exception_fp_ieee_invalid_op 0
		.amdhsa_exception_fp_denorm_src 0
		.amdhsa_exception_fp_ieee_div_zero 0
		.amdhsa_exception_fp_ieee_overflow 0
		.amdhsa_exception_fp_ieee_underflow 0
		.amdhsa_exception_fp_ieee_inexact 0
		.amdhsa_exception_int_div_zero 0
	.end_amdhsa_kernel

amdhsa.kernels:
  - .agpr_count:     0
    .args:
      - .offset:         0
        .size:           264
        .value_kind:     by_value
      - .offset:         264
        .size:           4
        .value_kind:     hidden_block_count_x
      - .offset:         268
        .size:           4
        .value_kind:     hidden_block_count_y
      - .offset:         272
        .size:           4
        .value_kind:     hidden_block_count_z
      - .offset:         276
        .size:           2
        .value_kind:     hidden_group_size_x
      - .offset:         278
        .size:           2
        .value_kind:     hidden_group_size_y
      - .offset:         280
        .size:           2
        .value_kind:     hidden_group_size_z
      - .offset:         282
        .size:           2
        .value_kind:     hidden_remainder_x
      - .offset:         284
        .size:           2
        .value_kind:     hidden_remainder_y
      - .offset:         286
        .size:           2
        .value_kind:     hidden_remainder_z
      - .offset:         304
        .size:           8
        .value_kind:     hidden_global_offset_x
      - .offset:         312
        .size:           8
        .value_kind:     hidden_global_offset_y
      - .offset:         320
        .size:           8
        .value_kind:     hidden_global_offset_z
      - .offset:         328
        .size:           2
        .value_kind:     hidden_grid_dims
      - .offset:         352
        .size:           8
        .value_kind:     hidden_multigrid_sync_arg
      - .offset:         384
        .size:           4
        .value_kind:     hidden_dynamic_lds_size
    .group_segment_fixed_size: 0
    .kernarg_segment_align: 8
    .kernarg_segment_size: 520
    .language:       OpenCL C
    .language_version:
      - 2
      - 0
    .max_flat_workgroup_size: 512
    .name:           _Z14fwd_megakernel4Args
    .private_segment_fixed_size: 0
    .sgpr_count:     106
    .sgpr_spill_count: 159
    .symbol:         _Z14fwd_megakernel4Args.kd
    .uniform_work_group_size: 1
    .uses_dynamic_stack: false
    .vgpr_count:     256
    .vgpr_spill_count: 0
    .wavefront_size: 64
